# NSA compressed-branch cross-lane max/sum reductions via v_permlane16/32_swap instead of ds_bpermute, on top of the top-k rewrite
# baseline (speedup 1.0000x reference)
; __device__ __forceinline__ f32x4 mfma16(bf16x8 a, bf16x8 b, f32x4 c) { return __builtin_amdgcn_mfma_f32_16x16x32_bf16(a, b, c, 0, 0, 0); }
; __device__ __forceinline__ f32x4 zero4() { return (f32x4){0.f, 0.f, 0.f, 0.f}; }
; __device__ __forceinline__ void nsa_tile(const Params& p, int qb, int bg, char* smem) {
;     ...
;         for (int i = 0; i < nkp; ++i) {
; #pragma unroll
;             for (int half = 0; half < 2; ++half) {
;                 const int kr = 32 * i + (fr >> 2) * 8 + half * 4 + (fr & 3);
;                 f32x4 s0 = zero4(), s1 = zero4();
; #pragma unroll
;                 for (int ks = 0; ks < 2; ++ks) {
;                     const bf16x8 kf = *(const bf16x8*)(smem + kr * 128 + ((ks * 4 + fq) ^ ((fr >> 1) & 7)) * 16);
;                     s0 = mfma16(kf, qf[0][ks], s0);
;                     s1 = mfma16(kf, qf[1][ks], s1);
;                 }
; #pragma unroll
;                 for (int qt = 0; qt < 2; ++qt) {
;                     const f32x4 sv = qt ? s1 : s0;
;                     float mx = -1e30f; float vals[4];
; #pragma unroll
;                     for (int jj = 0; jj < 4; ++jj) {
;                         const int nn = 32 * i + fq * 8 + half * 4 + jj;
;                         vals[jj] = (16 * nn + 31 <= tpos[qt]) ? sv[jj] : -1e30f;
;                         mx = fmaxf(mx, vals[jj]);
;                     }
;                     mx = fmaxf(mx, __shfl_xor(mx, 16));
;                     mx = fmaxf(mx, __shfl_xor(mx, 32));
;                     const float mnew = fmaxf(mc[qt], mx);
;                     float ps = 0.f;
; #pragma unroll
;                     for (int jj = 0; jj < 4; ++jj) ps += __builtin_amdgcn_exp2f(vals[jj] - mnew);
;                     ps += __shfl_xor(ps, 16);
;                     ps += __shfl_xor(ps, 32);
;                     lc[qt] = lc[qt] * __builtin_amdgcn_exp2f(mc[qt] - mnew) + ps;
;                     mc[qt] = mnew;
;                 }
;             }
;         }
.LBB0_348:
	ds_read_b128 v[20:23], v32
	ds_read_b128 v[34:37], v33
	ds_read_b128 v[42:45], v33 offset:512
	v_subrev_u32_e32 v29, 64, v0
	v_add_u32_e32 v48, -16, v0
	s_add_i32 s0, s0, -1
	v_add_u32_e32 v33, 0x1000, v33
	s_cmp_lg_u32 s0, 0
	s_waitcnt lgkmcnt(2)
	v_mfma_f32_16x16x32_bf16 v[24:27], v[20:23], v[4:7], 0
	v_mfma_f32_16x16x32_bf16 v[20:23], v[20:23], v[12:15], 0
	s_waitcnt lgkmcnt(1)
	v_mfma_f32_16x16x32_bf16 v[24:27], v[34:37], v[8:11], v[24:27]
	v_mfma_f32_16x16x32_bf16 v[34:37], v[34:37], v[16:19], v[20:23]
	s_nop 4
	v_add_u32_e32 v21, 0xffffff90, v0
	v_cmp_le_u32_e32 vcc, v21, v94
	v_add_u32_e32 v23, 0xffffffa0, v0
	s_nop 0
	v_cndmask_b32_e32 v20, v85, v24, vcc
	v_cmp_le_i32_e32 vcc, v23, v94
	s_nop 1
	v_cndmask_b32_e32 v24, v85, v25, vcc
	v_add_u32_e32 v25, 0xffffffb0, v0
	v_cmp_le_i32_e32 vcc, v25, v94
	v_max3_f32 v22, v20, s20, v24
	s_nop 0
	v_cndmask_b32_e32 v26, v85, v26, vcc
	v_cmp_le_i32_e32 vcc, v29, v94
	s_nop 1
	v_cndmask_b32_e32 v27, v85, v27, vcc
	v_max3_f32 v22, v22, v26, v27
	v_mov_b32_e32 v28, v22
	s_nop 1
	v_permlane16_swap_b32_e32 v22, v28
	v_cmp_le_u32_e32 vcc, v21, v92
	s_waitcnt lgkmcnt(0)
	v_max_f32_e32 v28, v28, v28
	v_max_f32_e32 v22, v22, v28
	v_mov_b32_e32 v28, v22
	s_nop 1
	v_permlane32_swap_b32_e32 v22, v28
	v_cndmask_b32_e32 v21, v85, v34, vcc
	v_cmp_le_i32_e32 vcc, v23, v92
	s_waitcnt lgkmcnt(0)
	v_max3_f32 v46, v98, v22, v28
	v_sub_f32_e32 v20, v20, v46
	v_exp_f32_e32 v22, v20
	v_sub_f32_e32 v20, v24, v46
	v_exp_f32_e32 v24, v20
	v_sub_f32_e32 v20, v26, v46
	v_exp_f32_e32 v26, v20
	v_sub_f32_e32 v20, v27, v46
	v_cndmask_b32_e32 v27, v85, v35, vcc
	v_cmp_le_i32_e32 vcc, v25, v92
	v_max3_f32 v23, v21, s20, v27
	v_exp_f32_e32 v28, v20
	v_cndmask_b32_e32 v34, v85, v36, vcc
	v_cmp_le_i32_e32 vcc, v29, v92
	v_sub_f32_e32 v20, v98, v46
	v_exp_f32_e32 v20, v20
	v_cndmask_b32_e32 v29, v85, v37, vcc
	v_max3_f32 v23, v23, v34, v29
	v_mov_b32_e32 v25, v23
	s_nop 1
	v_permlane16_swap_b32_e32 v23, v25
	s_waitcnt lgkmcnt(0)
	v_max_f32_e32 v25, v25, v25
	v_max_f32_e32 v23, v23, v25
	v_mov_b32_e32 v25, v23
	s_nop 1
	v_permlane32_swap_b32_e32 v23, v25
	s_waitcnt lgkmcnt(0)
	v_max3_f32 v47, v99, v23, v25
	v_sub_f32_e32 v21, v21, v47
	v_exp_f32_e32 v23, v21
	v_sub_f32_e32 v21, v27, v47
	v_exp_f32_e32 v25, v21
	v_sub_f32_e32 v21, v34, v47
	ds_read_b128 v[34:37], v32 offset:512
	s_waitcnt lgkmcnt(0)
	v_mfma_f32_16x16x32_bf16 v[38:41], v[34:37], v[4:7], 0
	v_exp_f32_e32 v27, v21
	v_sub_f32_e32 v21, v29, v47
	v_exp_f32_e32 v29, v21
	v_mfma_f32_16x16x32_bf16 v[34:37], v[34:37], v[12:15], 0
	v_add_f32_e64 v22, v22, 0
	v_add_f32_e64 v23, v23, 0
	v_sub_f32_e32 v21, v99, v47
	v_pk_add_f32 v[22:23], v[24:25], v[22:23]
	v_mfma_f32_16x16x32_bf16 v[38:41], v[42:45], v[8:11], v[38:41]
	v_add_f32_e64 v22, v26, v22
	v_add_f32_e64 v23, v27, v23
	v_exp_f32_e32 v21, v21
	v_pk_add_f32 v[22:23], v[28:29], v[22:23]
	v_mfma_f32_16x16x32_bf16 v[34:37], v[42:45], v[16:19], v[34:37]
	v_subrev_u32_e32 v43, 48, v0
	v_cmp_le_u32_e32 vcc, v43, v94
	v_subrev_u32_e32 v45, 32, v0
	v_mov_b32_e32 v24, v22
	s_nop 1
	v_permlane16_swap_b32_e32 v22, v24
	v_cndmask_b32_e32 v38, v85, v38, vcc
	v_cmp_le_i32_e32 vcc, v45, v94
	v_mov_b32_e32 v25, v23
	s_nop 1
	v_permlane16_swap_b32_e32 v23, v25
	v_add_u32_e32 v32, 0x1000, v32
	v_cndmask_b32_e32 v39, v85, v39, vcc
	v_cmp_le_i32_e32 vcc, v48, v94
	v_max3_f32 v42, v38, s20, v39
	s_waitcnt lgkmcnt(0)
	v_pk_add_f32 v[22:23], v[22:23], v[24:25]
	v_cndmask_b32_e32 v44, v85, v40, vcc
	v_cmp_le_i32_e32 vcc, v0, v94
	v_mov_b32_e32 v24, v22
	s_nop 1
	v_permlane32_swap_b32_e32 v22, v24
	v_mov_b32_e32 v25, v23
	s_nop 1
	v_permlane32_swap_b32_e32 v23, v25
	v_cndmask_b32_e32 v41, v85, v41, vcc
	v_max3_f32 v40, v42, v44, v41
	v_mov_b32_e32 v42, v40
	s_nop 1
	v_permlane16_swap_b32_e32 v40, v42
	v_cmp_le_i32_e32 vcc, v43, v92
	s_waitcnt lgkmcnt(1)
	v_pk_add_f32 v[22:23], v[22:23], v[24:25]
	s_waitcnt lgkmcnt(0)
	v_max_f32_e32 v42, v42, v42
	v_max_f32_e32 v40, v40, v42
	v_mov_b32_e32 v42, v40
	s_nop 1
	v_permlane32_swap_b32_e32 v40, v42
	v_cndmask_b32_e32 v34, v85, v34, vcc
	v_cmp_le_i32_e32 vcc, v45, v92
	v_pk_fma_f32 v[2:3], v[2:3], v[20:21], v[22:23]
	s_waitcnt lgkmcnt(0)
	v_max3_f32 v98, v46, v40, v42
	v_sub_f32_e32 v39, v39, v98
	v_exp_f32_e32 v40, v39
	v_sub_f32_e32 v39, v44, v98
	v_exp_f32_e32 v42, v39
	v_sub_f32_e32 v39, v41, v98
	v_cndmask_b32_e32 v35, v85, v35, vcc
	v_cmp_le_i32_e32 vcc, v48, v92
	v_exp_f32_e32 v44, v39
	v_sub_f32_e32 v39, v46, v98
	v_cndmask_b32_e32 v36, v85, v36, vcc
	v_cmp_le_i32_e32 vcc, v0, v92
	v_exp_f32_e32 v46, v39
	v_max3_f32 v39, v34, s20, v35
	v_cndmask_b32_e32 v37, v85, v37, vcc
	v_max3_f32 v39, v39, v36, v37
	v_mov_b32_e32 v41, v39
	s_nop 1
	v_permlane16_swap_b32_e32 v39, v41
	v_sub_f32_e32 v38, v38, v98
	v_exp_f32_e32 v38, v38
	v_add_u32_e32 v0, 0x200, v0
	s_waitcnt lgkmcnt(0)
	v_max_f32_e32 v41, v41, v41
	v_max_f32_e32 v39, v39, v41
	v_mov_b32_e32 v41, v39
	s_nop 1
	v_permlane32_swap_b32_e32 v39, v41
	s_waitcnt lgkmcnt(0)
	v_max3_f32 v99, v47, v39, v41
	v_sub_f32_e32 v34, v34, v99
	v_exp_f32_e32 v39, v34
	v_sub_f32_e32 v34, v35, v99
	v_exp_f32_e32 v41, v34
	v_sub_f32_e32 v34, v36, v99
	v_exp_f32_e32 v43, v34
	v_sub_f32_e32 v34, v37, v99
	v_exp_f32_e32 v45, v34
	v_pk_add_f32 v[20:21], v[38:39], 0 op_sel_hi:[1,0]
	v_sub_f32_e32 v34, v47, v99
	v_pk_add_f32 v[20:21], v[40:41], v[20:21]
	v_exp_f32_e32 v47, v34
	v_pk_add_f32 v[20:21], v[42:43], v[20:21]
	s_nop 0
	v_pk_add_f32 v[20:21], v[44:45], v[20:21]
	v_mov_b32_e32 v22, v20
	s_nop 1
	v_permlane16_swap_b32_e32 v20, v22
	v_mov_b32_e32 v23, v21
	s_nop 1
	v_permlane16_swap_b32_e32 v21, v23
	s_waitcnt lgkmcnt(0)
	v_pk_add_f32 v[20:21], v[20:21], v[22:23]
	v_mov_b32_e32 v22, v20
	s_nop 1
	v_permlane32_swap_b32_e32 v20, v22
	v_mov_b32_e32 v23, v21
	s_nop 1
	v_permlane32_swap_b32_e32 v21, v23
	s_waitcnt lgkmcnt(0)
	v_pk_add_f32 v[20:21], v[20:21], v[22:23]
	s_nop 0
	v_pk_fma_f32 v[2:3], v[2:3], v[46:47], v[20:21]
	s_cbranch_scc1 .LBB0_348
; __device__ __forceinline__ f32x4 zero4() { return (f32x4){0.f, 0.f, 0.f, 0.f}; }
; __device__ __forceinline__ void nsa_tile(const Params& p, int qb, int bg, char* smem) {
;     ...
;         const float il[2] = {1.0f / lc[0], 1.0f / lc[1]};
;         f32x4 Oc[2][4];
; #pragma unroll
;         for (int qt = 0; qt < 2; ++qt)
; #pragma unroll
;             for (int dt = 0; dt < 4; ++dt) Oc[qt][dt] = zero4();
;         float carry[2] = {0.f, 0.f};
; #pragma unroll 2
;         for (int i = 0; i < nkp; ++i) {
	v_div_scale_f32 v0, s[0:1], v2, v2, 1.0
	v_rcp_f32_e32 v20, v0
	v_div_scale_f32 v21, vcc, 1.0, v2, 1.0
	v_readlane_b32 s4, v244, 1
	v_fma_f32 v22, -v0, v20, 1.0
	v_fmac_f32_e32 v20, v22, v20
	v_mul_f32_e32 v22, v21, v20
	v_fma_f32 v23, -v0, v22, v21
	v_fmac_f32_e32 v22, v23, v20
	v_fma_f32 v0, -v0, v22, v21
	v_div_scale_f32 v21, s[0:1], v3, v3, 1.0
	v_rcp_f32_e32 v23, v21
	v_div_fmas_f32 v0, v0, v20, v22
	v_div_fixup_f32 v2, v0, v2, 1.0
	v_readlane_b32 s0, v244, 15
	v_fma_f32 v0, -v21, v23, 1.0
	v_fmac_f32_e32 v23, v0, v23
	v_div_scale_f32 v0, vcc, 1.0, v3, 1.0
	v_mul_f32_e32 v20, v0, v23
	v_fma_f32 v22, -v21, v20, v0
	v_fmac_f32_e32 v20, v22, v23
	v_fma_f32 v0, -v21, v20, v0
	v_div_fmas_f32 v0, v0, v23, v20
	v_div_fixup_f32 v60, v0, v3, 1.0
	v_add_u32_e32 v0, 48, v76
	v_and_or_b32 v0, v0, 63, v93
	v_and_b32_e32 v20, 32, v76
	v_lshlrev_b32_e32 v100, 2, v0
	v_or_b32_e32 v0, v30, v93
	v_lshlrev_b32_e32 v20, 6, v20
	v_mov_b32_e32 v21, v1
	v_lshl_or_b32 v101, v0, 2, v95
	v_lshlrev_b32_e32 v0, 5, v30
	v_lshl_add_u64 v[20:21], s[16:17], 0, v[20:21]
	v_lshl_add_u64 v[20:21], v[20:21], 0, v[0:1]
	v_and_b32_e32 v0, 16, v78
	s_cmp_gt_u32 s0, 31
	v_lshlrev_b32_e32 v22, 13, v80
	v_lshl_add_u64 v[20:21], v[20:21], 0, v[0:1]
	v_readlane_b32 s5, v244, 2
	v_or3_b32 v0, v22, v31, v90
	v_add_u32_e32 v102, 0x9000, v0
	v_lshl_add_u64 v[66:67], s[4:5], 0, v[20:21]
	s_cselect_b64 s[4:5], -1, 0
	v_mov_b32_e32 v103, 0
	v_cndmask_b32_e64 v0, 0, 1, s[4:5]
	v_cmp_gt_u32_e64 s[0:1], 16, v78
	v_mov_b32_e32 v63, v92
	v_mov_b32_e32 v61, v60
	v_mov_b32_e32 v3, v2
	v_mov_b32_e32 v65, v94
	v_cmp_ne_u32_e64 s[4:5], 1, v0
	v_mov_b32_e32 v104, 0
	v_mov_b32_e32 v20, 0
	v_mov_b32_e32 v21, v103
	v_mov_b32_e32 v22, v103
	v_mov_b32_e32 v23, v103
	v_mov_b32_e32 v24, 0
	v_mov_b32_e32 v25, v103
	v_mov_b32_e32 v26, v103
	v_mov_b32_e32 v27, v103
	v_mov_b32_e32 v36, 0
	v_mov_b32_e32 v37, v103
	v_mov_b32_e32 v38, v103
	v_mov_b32_e32 v39, v103
	v_mov_b32_e32 v32, 0
	v_mov_b32_e32 v33, v103
	v_mov_b32_e32 v34, v103
	v_mov_b32_e32 v35, v103
	v_mov_b32_e32 v28, 0
	v_mov_b32_e32 v29, v103
	v_mov_b32_e32 v30, v103
	v_mov_b32_e32 v31, v103
	v_mov_b32_e32 v40, 0
	v_mov_b32_e32 v41, v103
	v_mov_b32_e32 v42, v103
	v_mov_b32_e32 v43, v103
	v_mov_b32_e32 v48, 0
	v_mov_b32_e32 v49, v103
	v_mov_b32_e32 v50, v103
	v_mov_b32_e32 v51, v103
	v_mov_b32_e32 v44, 0
	v_mov_b32_e32 v45, v103
	v_mov_b32_e32 v46, v103
	v_mov_b32_e32 v47, v103
	s_branch .LBB0_351
